# mixers co-scheduling variant: second WG of each CU swaps its MLA and NA rounds (MLA rounds in natural order 0,1,2,3 after NA)
# speedup vs baseline: 1.0038x; 1.0031x over previous
.LBB0_209:
	v_writelane_b32 v221, s20, 61
	s_movk_i32 s1, 0x800
	s_cmpk_lt_u32 s20, 0x1000
	s_cselect_b32 s1, s1, 0
	s_getreg_b32 s0, hwreg(HW_REG_LDS_ALLOC, 0, 8)
	s_cmp_lg_u32 s0, 0
	s_cselect_b32 s1, s1, 0
	s_xor_b32 s20, s20, s1
	s_cmp_ge_i32 s20, s14
	s_mov_b64 s[0:1], -1
	s_cbranch_scc0 .LBB0_211
	s_sub_i32 s0, s20, s14
	s_lshl_b32 s0, s0, 5
	v_mov_b32_e32 v10, v196
	s_and_b32 s2, s0, 0x7fffff80
	s_and_b32 s5, s20, 3
	v_lshrrev_b32_e32 v0, 2, v10
	s_lshl_b64 s[0:1], s[2:3], 10
	v_and_b32_e32 v0, 12, v0
	s_add_u32 s2, s15, s0
	v_lshrrev_b32_e64 v0, v0, s57
	s_addc_u32 s7, s21, s1
	s_lshl_b32 s4, s5, 8
	v_xor_b32_e32 v0, v0, v10
	s_add_u32 s6, s2, s4
	v_ashrrev_i32_e32 v2, 2, v10
	v_lshlrev_b32_e32 v0, 4, v0
	s_addc_u32 s7, s7, 0
	v_and_b32_e32 v0, 48, v0
	v_ashrrev_i32_e32 v3, 31, v2
	v_lshl_add_u64 v[4:5], s[6:7], 0, v[0:1]
	v_lshlrev_b64 v[6:7], 10, v[2:3]
	v_lshl_add_u64 v[70:71], v[4:5], 0, v[6:7]
	v_add_u32_e32 v6, 64, v2
	s_lshl_b32 s2, s5, 15
	v_readlane_b32 s8, v224, 11
	v_ashrrev_i32_e32 v7, 31, v6
	s_add_u32 s8, s8, s2
	v_readlane_b32 s2, v224, 12
	v_lshlrev_b64 v[8:9], 10, v[6:7]
	s_addc_u32 s9, s2, 0
	v_lshl_add_u64 v[72:73], v[4:5], 0, v[8:9]
	v_and_b32_e32 v8, 15, v10
	v_lshlrev_b64 v[4:5], 8, v[6:7]
	v_lshl_add_u32 v12, v10, 4, 0
	v_lshrrev_b32_e32 v6, 1, v10
	s_mov_b32 s2, 0x3ffffc0
	v_lshlrev_b64 v[2:3], 8, v[2:3]
	v_and_or_b32 v13, v6, s2, v8
	v_readfirstlane_b32 s2, v12
	v_add_u32_e32 v8, 0x1000, v12
	v_lshl_add_u64 v[2:3], s[8:9], 0, v[2:3]
	v_and_b32_e32 v6, 12, v10
	s_mov_b32 m0, s2
	v_readfirstlane_b32 s6, v8
	v_lshl_add_u64 v[74:75], v[2:3], 0, v[0:1]
	v_add_u32_e32 v2, 0x2000, v12
	v_lshrrev_b32_e32 v11, 4, v10
	v_lshl_add_u64 v[4:5], s[8:9], 0, v[4:5]
	v_lshrrev_b32_e64 v6, v6, s57
	global_load_lds_dwordx4 v[70:71], off
	s_mov_b32 m0, s6
	v_readfirstlane_b32 s7, v2
	v_add_u32_e32 v2, 0x3000, v12
	v_xor_b32_e32 v6, v6, v11
	global_load_lds_dwordx4 v[72:73], off
	v_lshl_add_u64 v[76:77], v[4:5], 0, v[0:1]
	s_mov_b32 m0, s7
	v_readfirstlane_b32 s8, v2
	v_add_u32_e32 v4, 0x4000, v12
	v_lshlrev_b32_e32 v11, 4, v6
	v_lshlrev_b32_e32 v6, 6, v10
	global_load_lds_dwordx4 v[74:75], off
	s_mov_b32 m0, s8
	v_readfirstlane_b32 s9, v4
	v_and_b32_e32 v10, 0x13c0, v6
	v_lshl_add_u64 v[6:7], v[70:71], 0, 64
	global_load_lds_dwordx4 v[76:77], off
	s_mov_b32 m0, s9
	v_add_u32_e32 v4, 0x5000, v12
	global_load_lds_dwordx4 v[6:7], off
	v_readfirstlane_b32 s9, v4
	v_add_u32_e32 v6, 0x6000, v12
	v_lshl_add_u64 v[8:9], v[72:73], 0, 64
	s_mov_b32 m0, s9
	v_readfirstlane_b32 s9, v6
	v_lshl_add_u64 v[2:3], v[74:75], 0, 64
	global_load_lds_dwordx4 v[8:9], off
	s_mov_b32 m0, s9
	v_and_b32_e32 v0, 48, v11
	global_load_lds_dwordx4 v[2:3], off
	v_add_u32_e32 v2, 0x7000, v12
	v_lshl_add_u64 v[4:5], v[76:77], 0, 64
	v_readfirstlane_b32 s9, v2
	s_mov_b32 m0, s9
	v_add_u32_e32 v11, 0x8000, v12
	global_load_lds_dwordx4 v[4:5], off
	v_add_u32_e32 v14, 0xb000, v12
	v_add_u32_e32 v15, 0xa000, v12
	v_add_u32_e32 v12, 0x9000, v12
	v_readfirstlane_b32 s9, v11
	s_waitcnt vmcnt(4) lgkmcnt(0)
	s_barrier
	v_lshl_add_u64 v[2:3], v[70:71], 0, s[78:79]
	s_mov_b32 m0, s9
	v_readfirstlane_b32 s9, v12
	v_lshl_add_u64 v[4:5], v[72:73], 0, s[78:79]
	global_load_lds_dwordx4 v[2:3], off
	s_mov_b32 m0, s9
	v_readfirstlane_b32 s9, v15
	v_lshl_add_u64 v[8:9], v[74:75], 0, s[78:79]
	global_load_lds_dwordx4 v[4:5], off
	s_mov_b32 m0, s9
	v_readfirstlane_b32 s9, v14
	v_lshl_add_u64 v[6:7], v[76:77], 0, s[78:79]
	global_load_lds_dwordx4 v[8:9], off
	s_mov_b32 m0, s9
	v_add3_u32 v90, 0, v10, v0
	v_lshlrev_b32_e32 v10, 6, v13
	global_load_lds_dwordx4 v[6:7], off
	v_add3_u32 v0, 0, v10, v0
	ds_read_b128 v[2:5], v90 offset:8192
	ds_read_b128 v[6:9], v90 offset:9216
	ds_read_b128 v[10:13], v0
	ds_read_b128 v[14:17], v0 offset:1024
	ds_read_b128 v[22:25], v90 offset:10240
	ds_read_b128 v[30:33], v90 offset:11264
	ds_read_b128 v[50:53], v0 offset:2048
	ds_read_b128 v[54:57], v0 offset:3072
	v_lshl_add_u64 v[70:71], v[70:71], 0, s[84:85]
	s_waitcnt vmcnt(4) lgkmcnt(0)
	s_barrier
	s_mov_b32 m0, s2
	v_lshl_add_u64 v[72:73], v[72:73], 0, s[84:85]
	global_load_lds_dwordx4 v[70:71], off
	s_mov_b32 m0, s6
	v_lshl_add_u64 v[74:75], v[74:75], 0, s[84:85]
	global_load_lds_dwordx4 v[72:73], off
	s_mov_b32 m0, s7
	v_lshl_add_u64 v[76:77], v[76:77], 0, s[84:85]
	global_load_lds_dwordx4 v[74:75], off
	s_mov_b32 m0, s8
	s_waitcnt lgkmcnt(0)
	s_setprio 1
	v_mfma_f32_16x16x32_bf16 v[18:21], v[2:5], v[10:13], 0
	global_load_lds_dwordx4 v[76:77], off
	s_setprio 0
	ds_read_b128 v[70:73], v90 offset:24576
	s_setprio 1
	v_mfma_f32_16x16x32_bf16 v[26:29], v[6:9], v[10:13], 0
	s_lshl_b32 s2, s5, 9
	v_lshl_add_u64 v[94:95], v[146:147], 0, s[2:3]
	v_readlane_b32 s2, v224, 1
	v_mfma_f32_16x16x32_bf16 v[34:37], v[22:25], v[10:13], 0
	s_add_u32 s0, s2, s0
	v_readlane_b32 s2, v224, 2
	s_addc_u32 s1, s2, s1
	v_mfma_f32_16x16x32_bf16 v[10:13], v[30:33], v[10:13], 0
	s_mov_b32 s2, 0xfffffc0
	s_add_u32 s0, s0, s4
	s_addc_u32 s1, s1, 0
	v_mfma_f32_16x16x32_bf16 v[38:41], v[2:5], v[14:17], 0
	v_mfma_f32_16x16x32_bf16 v[42:45], v[6:9], v[14:17], 0
	v_mfma_f32_16x16x32_bf16 v[46:49], v[22:25], v[14:17], 0
	v_mfma_f32_16x16x32_bf16 v[14:17], v[30:33], v[14:17], 0
	v_mfma_f32_16x16x32_bf16 v[58:61], v[2:5], v[50:53], 0
	v_mfma_f32_16x16x32_bf16 v[62:65], v[6:9], v[50:53], 0
	v_mfma_f32_16x16x32_bf16 v[66:69], v[22:25], v[50:53], 0
	v_mfma_f32_16x16x32_bf16 v[50:53], v[30:33], v[50:53], 0
	v_mfma_f32_16x16x32_bf16 v[2:5], v[2:5], v[54:57], 0
	v_mfma_f32_16x16x32_bf16 v[6:9], v[6:9], v[54:57], 0
	v_mfma_f32_16x16x32_bf16 v[22:25], v[22:25], v[54:57], 0
	v_mfma_f32_16x16x32_bf16 v[30:33], v[30:33], v[54:57], 0
	s_setprio 0
	ds_read_b128 v[54:57], v90 offset:25600
	ds_read_b128 v[74:77], v0 offset:16384
	ds_read_b128 v[78:81], v0 offset:17408
	ds_read_b128 v[82:85], v90 offset:26624
	ds_read_b128 v[86:89], v90 offset:27648
	s_waitcnt lgkmcnt(0)
	s_setprio 1
	v_mfma_f32_16x16x32_bf16 v[18:21], v[70:73], v[74:77], v[18:21]
	v_mfma_f32_16x16x32_bf16 v[26:29], v[54:57], v[74:77], v[26:29]
	v_mfma_f32_16x16x32_bf16 v[34:37], v[82:85], v[74:77], v[34:37]
	v_mfma_f32_16x16x32_bf16 v[10:13], v[86:89], v[74:77], v[10:13]
	v_mfma_f32_16x16x32_bf16 v[38:41], v[70:73], v[78:81], v[38:41]
	v_mfma_f32_16x16x32_bf16 v[42:45], v[54:57], v[78:81], v[42:45]
	v_mfma_f32_16x16x32_bf16 v[46:49], v[82:85], v[78:81], v[46:49]
	v_mfma_f32_16x16x32_bf16 v[14:17], v[86:89], v[78:81], v[14:17]
	s_setprio 0
	ds_read_b128 v[74:77], v0 offset:18432
	ds_read_b128 v[78:81], v0 offset:19456
	s_waitcnt vmcnt(4) lgkmcnt(0)
	s_barrier
	s_waitcnt lgkmcnt(0)
	s_setprio 1
	v_mfma_f32_16x16x32_bf16 v[58:61], v[70:73], v[74:77], v[58:61]
	v_mfma_f32_16x16x32_bf16 v[62:65], v[54:57], v[74:77], v[62:65]
	v_mfma_f32_16x16x32_bf16 v[66:69], v[82:85], v[74:77], v[66:69]
	v_mfma_f32_16x16x32_bf16 v[50:53], v[86:89], v[74:77], v[50:53]
	v_mfma_f32_16x16x32_bf16 v[2:5], v[70:73], v[78:81], v[2:5]
	v_mfma_f32_16x16x32_bf16 v[6:9], v[54:57], v[78:81], v[6:9]
	s_setprio 0
	ds_read_b128 v[54:57], v90 offset:40960
	s_setprio 1
	v_mfma_f32_16x16x32_bf16 v[22:25], v[82:85], v[78:81], v[22:25]
	v_mfma_f32_16x16x32_bf16 v[30:33], v[86:89], v[78:81], v[30:33]
	s_setprio 0
	ds_read_b128 v[70:73], v90 offset:41984
	ds_read_b128 v[74:77], v0 offset:32768
	ds_read_b128 v[78:81], v0 offset:33792
	ds_read_b128 v[82:85], v90 offset:43008
	ds_read_b128 v[86:89], v90 offset:44032
	s_waitcnt lgkmcnt(0)
	s_setprio 1
	v_mfma_f32_16x16x32_bf16 v[18:21], v[54:57], v[74:77], v[18:21]
	v_mfma_f32_16x16x32_bf16 v[26:29], v[70:73], v[74:77], v[26:29]
	v_mfma_f32_16x16x32_bf16 v[34:37], v[82:85], v[74:77], v[34:37]
	v_mfma_f32_16x16x32_bf16 v[10:13], v[86:89], v[74:77], v[10:13]
	v_mfma_f32_16x16x32_bf16 v[38:41], v[54:57], v[78:81], v[38:41]
	v_mfma_f32_16x16x32_bf16 v[42:45], v[70:73], v[78:81], v[42:45]
	v_mfma_f32_16x16x32_bf16 v[46:49], v[82:85], v[78:81], v[46:49]
	v_mfma_f32_16x16x32_bf16 v[14:17], v[86:89], v[78:81], v[14:17]
	s_setprio 0
	ds_read_b128 v[74:77], v0 offset:34816
	ds_read_b128 v[78:81], v0 offset:35840
	s_waitcnt vmcnt(0) lgkmcnt(0)
	s_barrier
	s_waitcnt lgkmcnt(0)
	s_setprio 1
	v_mfma_f32_16x16x32_bf16 v[58:61], v[54:57], v[74:77], v[58:61]
	v_mfma_f32_16x16x32_bf16 v[62:65], v[70:73], v[74:77], v[62:65]
	v_mfma_f32_16x16x32_bf16 v[66:69], v[82:85], v[74:77], v[66:69]
	v_mfma_f32_16x16x32_bf16 v[50:53], v[86:89], v[74:77], v[50:53]
	v_mfma_f32_16x16x32_bf16 v[2:5], v[54:57], v[78:81], v[2:5]
	s_setprio 0
	ds_read_b128 v[54:57], v90 offset:8192
	s_setprio 1
	v_mfma_f32_16x16x32_bf16 v[6:9], v[70:73], v[78:81], v[6:9]
	v_mfma_f32_16x16x32_bf16 v[22:25], v[82:85], v[78:81], v[22:25]
	v_mfma_f32_16x16x32_bf16 v[30:33], v[86:89], v[78:81], v[30:33]
	s_setprio 0
	ds_read_b128 v[70:73], v90 offset:9216
	ds_read_b128 v[74:77], v0
	ds_read_b128 v[78:81], v0 offset:1024
	ds_read_b128 v[82:85], v90 offset:10240
	ds_read_b128 v[86:89], v90 offset:11264
	s_waitcnt lgkmcnt(0)
	s_setprio 1
	v_mfma_f32_16x16x32_bf16 v[18:21], v[54:57], v[74:77], v[18:21]
	v_mfma_f32_16x16x32_bf16 v[26:29], v[70:73], v[74:77], v[26:29]
	v_mfma_f32_16x16x32_bf16 v[34:37], v[82:85], v[74:77], v[34:37]
	v_mfma_f32_16x16x32_bf16 v[10:13], v[86:89], v[74:77], v[10:13]
	v_mfma_f32_16x16x32_bf16 v[38:41], v[54:57], v[78:81], v[38:41]
	v_mfma_f32_16x16x32_bf16 v[42:45], v[70:73], v[78:81], v[42:45]
	v_mfma_f32_16x16x32_bf16 v[46:49], v[82:85], v[78:81], v[46:49]
	v_mfma_f32_16x16x32_bf16 v[14:17], v[86:89], v[78:81], v[14:17]
	s_setprio 0
	ds_read_b128 v[74:77], v0 offset:2048
	ds_read_b128 v[78:81], v0 offset:3072
	s_waitcnt vmcnt(0) lgkmcnt(0)
	s_barrier
	s_setprio 1
	v_mfma_f32_16x16x32_bf16 v[58:61], v[54:57], v[74:77], v[58:61]
	global_load_dwordx4 v[90:93], v[94:95], off
	v_mfma_f32_16x16x32_bf16 v[2:5], v[54:57], v[78:81], v[2:5]
	global_load_dwordx4 v[54:57], v[94:95], off offset:128
	v_mfma_f32_16x16x32_bf16 v[62:65], v[70:73], v[74:77], v[62:65]
	v_mfma_f32_16x16x32_bf16 v[66:69], v[82:85], v[74:77], v[66:69]
	v_mfma_f32_16x16x32_bf16 v[50:53], v[86:89], v[74:77], v[50:53]
	global_load_dwordx4 v[74:77], v[94:95], off offset:64
	s_setprio 0
	s_waitcnt vmcnt(2)
	v_pk_mul_f32 v[18:19], v[18:19], v[90:91]
	s_setprio 1
	v_mfma_f32_16x16x32_bf16 v[6:9], v[70:73], v[78:81], v[6:9]
	global_load_dwordx4 v[70:73], v[94:95], off offset:192
	s_setprio 0
	s_waitcnt vmcnt(2)
	v_pk_mul_f32 v[34:35], v[34:35], v[54:55]
	v_pk_mul_f32 v[46:47], v[46:47], v[54:55]
	s_setprio 1
	v_mfma_f32_16x16x32_bf16 v[22:25], v[82:85], v[78:81], v[22:25]
	v_mul_f32_e64 v66, v66, v54
	v_mul_f32_e64 v67, v67, v55
	v_pk_mul_f32 v[36:37], v[36:37], v[56:57]
	v_pk_mul_f32 v[48:49], v[48:49], v[56:57]
	v_mfma_f32_16x16x32_bf16 v[30:33], v[86:89], v[78:81], v[30:33]
	v_mul_f32_e64 v20, v20, v92
	v_mul_f32_e64 v21, v21, v93
	s_nop 0
	v_pk_mul_f32 v[22:23], v[22:23], v[54:55]
	v_pk_mul_f32 v[54:55], v[68:69], v[56:57]
	v_pk_mul_f32 v[24:25], v[24:25], v[56:57]
	v_mov_b32_e32 v56, v196
	s_setprio 0
	s_waitcnt vmcnt(1)
	v_pk_mul_f32 v[26:27], v[26:27], v[74:75]
	v_and_b32_e32 v57, 15, v56
	v_lshrrev_b32_e32 v68, 1, v56
	v_and_b32_e32 v0, 64, v56
	v_and_or_b32 v69, v68, s2, v57
	v_pk_mul_f32 v[28:29], v[28:29], v[76:77]
	v_lshl_add_u32 v0, v0, 1, 0
	v_and_b32_e32 v68, 24, v68
	v_mul_lo_u32 v69, v69, s30
	v_add3_u32 v0, v0, v68, v69
	v_cvt_pk_bf16_f32 v18, v18, v19
	v_cvt_pk_bf16_f32 v19, v20, v21
	v_cvt_pk_bf16_f32 v20, v26, v27
	v_cvt_pk_bf16_f32 v21, v28, v29
	v_pk_mul_f32 v[38:39], v[38:39], v[90:91]
	v_pk_mul_f32 v[40:41], v[40:41], v[92:93]
	v_pk_mul_f32 v[42:43], v[42:43], v[74:75]
	v_pk_mul_f32 v[44:45], v[44:45], v[76:77]
	ds_write2_b64 v0, v[18:19], v[20:21] offset1:4
	v_cvt_pk_bf16_f32 v18, v34, v35
	v_cvt_pk_bf16_f32 v19, v36, v37
	v_pk_mul_f32 v[2:3], v[2:3], v[90:91]
	v_pk_mul_f32 v[4:5], v[4:5], v[92:93]
	v_pk_mul_f32 v[6:7], v[6:7], v[74:75]
	v_pk_mul_f32 v[8:9], v[8:9], v[76:77]
	v_pk_mul_f32 v[58:59], v[58:59], v[90:91]
	v_pk_mul_f32 v[60:61], v[60:61], v[92:93]
	v_pk_mul_f32 v[62:63], v[62:63], v[74:75]
	v_pk_mul_f32 v[64:65], v[64:65], v[76:77]
	v_cvt_pk_bf16_f32 v2, v2, v3
	v_cvt_pk_bf16_f32 v3, v4, v5
	v_cvt_pk_bf16_f32 v4, v6, v7
	v_cvt_pk_bf16_f32 v5, v8, v9
	v_add_u32_e32 v6, 0x100, v56
	s_waitcnt vmcnt(0)
	v_pk_mul_f32 v[10:11], v[10:11], v[70:71]
	v_pk_mul_f32 v[12:13], v[12:13], v[72:73]
	v_cvt_pk_bf16_f32 v10, v10, v11
	v_cvt_pk_bf16_f32 v11, v12, v13
	v_pk_mul_f32 v[14:15], v[14:15], v[70:71]
	v_pk_mul_f32 v[16:17], v[16:17], v[72:73]
	ds_write2_b64 v0, v[18:19], v[10:11] offset0:8 offset1:12
	v_cvt_pk_bf16_f32 v10, v38, v39
	v_cvt_pk_bf16_f32 v11, v40, v41
	v_cvt_pk_bf16_f32 v12, v42, v43
	v_cvt_pk_bf16_f32 v13, v44, v45
	v_add_u32_e32 v18, 0x1000, v0
	v_pk_mul_f32 v[30:31], v[30:31], v[70:71]
	v_pk_mul_f32 v[32:33], v[32:33], v[72:73]
	ds_write2_b64 v18, v[10:11], v[12:13] offset0:32 offset1:36
	v_cvt_pk_bf16_f32 v10, v46, v47
	v_cvt_pk_bf16_f32 v11, v48, v49
	v_cvt_pk_bf16_f32 v12, v14, v15
	v_cvt_pk_bf16_f32 v13, v16, v17
	v_add_u32_e32 v14, 0x2000, v0
	v_add_u32_e32 v0, 0x3000, v0
	v_pk_mul_f32 v[50:51], v[50:51], v[70:71]
	v_pk_mul_f32 v[52:53], v[52:53], v[72:73]
	ds_write2_b64 v18, v[10:11], v[12:13] offset0:40 offset1:44
	v_cvt_pk_bf16_f32 v10, v58, v59
	v_cvt_pk_bf16_f32 v11, v60, v61
	v_cvt_pk_bf16_f32 v12, v62, v63
	v_cvt_pk_bf16_f32 v13, v64, v65
	ds_write2_b64 v0, v[2:3], v[4:5] offset0:96 offset1:100
	v_cvt_pk_bf16_f32 v2, v22, v23
	v_cvt_pk_bf16_f32 v3, v24, v25
	v_cvt_pk_bf16_f32 v4, v30, v31
	v_cvt_pk_bf16_f32 v5, v32, v33
	ds_write2_b64 v14, v[10:11], v[12:13] offset0:64 offset1:68
	v_cvt_pk_bf16_f32 v10, v66, v67
	v_cvt_pk_bf16_f32 v11, v54, v55
	v_cvt_pk_bf16_f32 v12, v50, v51
	v_cvt_pk_bf16_f32 v13, v52, v53
	ds_write2_b64 v0, v[2:3], v[4:5] offset0:104 offset1:108
	v_lshlrev_b32_e32 v0, 4, v57
	v_ashrrev_i32_e32 v2, 4, v56
	ds_write2_b64 v14, v[10:11], v[12:13] offset0:72 offset1:76
	v_lshl_add_u64 v[10:11], s[0:1], 0, v[0:1]
	v_add_u32_e32 v0, 0, v0
	v_ashrrev_i32_e32 v3, 31, v2
	v_mad_u64_u32 v[4:5], s[0:1], v2, s30, v[0:1]
	v_lshlrev_b64 v[2:3], 10, v[2:3]
	s_waitcnt lgkmcnt(0)
	s_barrier
	v_lshl_add_u64 v[12:13], v[10:11], 0, v[2:3]
	ds_read_b128 v[2:5], v4
	v_ashrrev_i32_e32 v14, 4, v6
	v_mad_u64_u32 v[6:7], s[0:1], v14, s30, v[0:1]
	ds_read_b128 v[6:9], v6
	v_ashrrev_i32_e32 v15, 31, v14
	s_waitcnt lgkmcnt(1)
	global_store_dwordx4 v[12:13], v[2:5], off
	s_nop 1
	v_lshlrev_b64 v[2:3], 10, v[14:15]
	v_lshl_add_u64 v[2:3], v[10:11], 0, v[2:3]
	s_waitcnt lgkmcnt(0)
	global_store_dwordx4 v[2:3], v[6:9], off
	v_add_u32_e32 v2, 0x200, v56
	v_ashrrev_i32_e32 v2, 4, v2
	v_ashrrev_i32_e32 v3, 31, v2
	v_mad_u64_u32 v[4:5], s[0:1], v2, s30, v[0:1]
	v_lshlrev_b64 v[2:3], 10, v[2:3]
	v_add_u32_e32 v6, 0x300, v56
	v_lshl_add_u64 v[12:13], v[10:11], 0, v[2:3]
	ds_read_b128 v[2:5], v4
	v_ashrrev_i32_e32 v14, 4, v6
	v_mad_u64_u32 v[6:7], s[0:1], v14, s30, v[0:1]
	ds_read_b128 v[6:9], v6
	v_ashrrev_i32_e32 v15, 31, v14
	s_waitcnt lgkmcnt(1)
	global_store_dwordx4 v[12:13], v[2:5], off
	s_nop 1
	v_lshlrev_b64 v[2:3], 10, v[14:15]
	v_lshl_add_u64 v[2:3], v[10:11], 0, v[2:3]
	s_waitcnt lgkmcnt(0)
	global_store_dwordx4 v[2:3], v[6:9], off
	v_add_u32_e32 v2, 0x400, v56
	v_ashrrev_i32_e32 v2, 4, v2
	v_ashrrev_i32_e32 v3, 31, v2
	v_mad_u64_u32 v[4:5], s[0:1], v2, s30, v[0:1]
	v_lshlrev_b64 v[2:3], 10, v[2:3]
	v_add_u32_e32 v6, 0x500, v56
	v_lshl_add_u64 v[12:13], v[10:11], 0, v[2:3]
	ds_read_b128 v[2:5], v4
	v_ashrrev_i32_e32 v14, 4, v6
	v_mad_u64_u32 v[6:7], s[0:1], v14, s30, v[0:1]
	ds_read_b128 v[6:9], v6
	v_ashrrev_i32_e32 v15, 31, v14
	s_waitcnt lgkmcnt(1)
	global_store_dwordx4 v[12:13], v[2:5], off
	s_nop 1
	v_lshlrev_b64 v[2:3], 10, v[14:15]
	v_lshl_add_u64 v[2:3], v[10:11], 0, v[2:3]
	s_waitcnt lgkmcnt(0)
	global_store_dwordx4 v[2:3], v[6:9], off
	v_add_u32_e32 v2, 0x600, v56
	v_ashrrev_i32_e32 v2, 4, v2
	v_ashrrev_i32_e32 v3, 31, v2
	v_mad_u64_u32 v[4:5], s[0:1], v2, s30, v[0:1]
	v_lshlrev_b64 v[2:3], 10, v[2:3]
	v_add_u32_e32 v6, 0x700, v56
	v_lshl_add_u64 v[12:13], v[10:11], 0, v[2:3]
	ds_read_b128 v[2:5], v4
	v_ashrrev_i32_e32 v14, 4, v6
	v_mad_u64_u32 v[6:7], s[0:1], v14, s30, v[0:1]
	ds_read_b128 v[6:9], v6
	v_ashrrev_i32_e32 v15, 31, v14
	s_waitcnt lgkmcnt(1)
	global_store_dwordx4 v[12:13], v[2:5], off
	s_mov_b64 s[0:1], 0
	s_nop 0
	v_lshlrev_b64 v[2:3], 10, v[14:15]
	v_lshl_add_u64 v[2:3], v[10:11], 0, v[2:3]
	s_waitcnt lgkmcnt(0)
	global_store_dwordx4 v[2:3], v[6:9], off
	s_barrier
